# ret_out epilogue: gate rows and GroupNorm weights prefetched, counted waits no longer drain the RA stores
# speedup vs baseline: 1.0613x; 1.0089x over previous
; __device__ __forceinline__ float shx(float v, int lane, int m) { return __builtin_bit_cast(float, __builtin_amdgcn_ds_bpermute((lane ^ m) << 2, __builtin_bit_cast(int, v))); }
; __device__ __forceinline__ void ret_out_item(const Params& p, int l, LAS unsigned char* lds, int item, int tid, int wave, int lane) {
;     ...
;     float sum = 0.f;
; #pragma unroll
;     for (int i = 0; i < 16; ++i) sum += (o[i][0] + o[i][1]) + (o[i][2] + o[i][3]);
;     sum += shx(sum, lane, 16); sum += shx(sum, lane, 32);
;     const float mu = sum * (1.f / 256.f);
;     float vs = 0.f;
; #pragma unroll
;     for (int i = 0; i < 16; ++i) { o[i] = o[i] - mu; vs += (o[i][0] * o[i][0] + o[i][1] * o[i][1]) + (o[i][2] * o[i][2] + o[i][3] * o[i][3]); }
;     vs += shx(vs, lane, 16); vs += shx(vs, lane, 32);
.LBB0_522:
	v_mov_b32_e32 v68, v65
	v_mov_b32_e32 v69, v66
	v_mov_b32_e32 v70, v64
	v_mov_b32_e32 v71, v67
	v_pk_add_f32 v[68:69], v[68:69], v[70:71]
	v_mov_b32_e32 v70, v61
	v_mov_b32_e32 v71, v62
	v_mov_b32_e32 v72, v60
	v_mov_b32_e32 v73, v63
	v_pk_add_f32 v[70:71], v[70:71], v[72:73]
	v_add_f32_e32 v68, v68, v69
	v_pk_add_f32 v[70:71], v[70:71], v[70:71] op_sel_hi:[0,1]
	v_add_f32_e32 v69, 0, v68
	v_add_f32_e32 v73, v44, v45
	v_add_f32_e32 v75, v46, v47
	v_mov_b32_e32 v72, v48
	v_mov_b32_e32 v74, v49
	v_mov_b32_e32 v70, v50
	v_mov_b32_e32 v68, v51
	v_pk_add_f32 v[72:73], v[72:73], v[74:75]
	v_pk_add_f32 v[68:69], v[70:71], v[68:69]
	v_mov_b32_e32 v70, v57
	v_pk_add_f32 v[68:69], v[72:73], v[68:69]
	v_mov_b32_e32 v71, v58
	v_mov_b32_e32 v72, v56
	v_mov_b32_e32 v73, v59
	v_pk_add_f32 v[70:71], v[70:71], v[72:73]
	v_pk_add_f32 v[68:69], v[68:69], v[68:69] op_sel_hi:[0,1]
	v_pk_add_f32 v[70:71], v[70:71], v[70:71] op_sel_hi:[0,1]
	v_add_f32_e32 v73, v52, v53
	v_add_f32_e32 v75, v54, v55
	v_mov_b32_e32 v72, v36
	v_mov_b32_e32 v74, v37
	v_mov_b32_e32 v70, v38
	v_mov_b32_e32 v68, v39
	v_pk_add_f32 v[72:73], v[72:73], v[74:75]
	v_pk_add_f32 v[68:69], v[70:71], v[68:69]
	v_mov_b32_e32 v70, v41
	v_pk_add_f32 v[68:69], v[72:73], v[68:69]
	v_mov_b32_e32 v71, v42
	v_mov_b32_e32 v72, v40
	v_mov_b32_e32 v73, v43
	v_pk_add_f32 v[70:71], v[70:71], v[72:73]
	v_pk_add_f32 v[68:69], v[68:69], v[68:69] op_sel_hi:[0,1]
	v_pk_add_f32 v[70:71], v[70:71], v[70:71] op_sel_hi:[0,1]
	v_add_f32_e32 v73, v32, v33
	v_add_f32_e32 v75, v34, v35
	v_mov_b32_e32 v72, v28
	v_mov_b32_e32 v74, v29
	v_mov_b32_e32 v70, v30
	v_mov_b32_e32 v68, v31
	v_pk_add_f32 v[72:73], v[72:73], v[74:75]
	v_pk_add_f32 v[68:69], v[70:71], v[68:69]
	v_mov_b32_e32 v70, v21
	v_pk_add_f32 v[68:69], v[72:73], v[68:69]
	v_mov_b32_e32 v71, v22
	v_mov_b32_e32 v72, v20
	v_mov_b32_e32 v73, v23
	v_pk_add_f32 v[70:71], v[70:71], v[72:73]
	v_pk_add_f32 v[68:69], v[68:69], v[68:69] op_sel_hi:[0,1]
	v_pk_add_f32 v[70:71], v[70:71], v[70:71] op_sel_hi:[0,1]
	v_add_f32_e32 v73, v24, v25
	v_add_f32_e32 v75, v26, v27
	v_mov_b32_e32 v72, v16
	v_mov_b32_e32 v74, v17
	v_mov_b32_e32 v70, v18
	v_mov_b32_e32 v68, v19
	v_pk_add_f32 v[72:73], v[72:73], v[74:75]
	v_pk_add_f32 v[68:69], v[70:71], v[68:69]
	v_mov_b32_e32 v70, v13
	v_pk_add_f32 v[68:69], v[72:73], v[68:69]
	v_mov_b32_e32 v71, v14
	v_mov_b32_e32 v72, v12
	v_mov_b32_e32 v73, v15
	v_pk_add_f32 v[70:71], v[70:71], v[72:73]
	v_pk_add_f32 v[68:69], v[68:69], v[68:69] op_sel_hi:[0,1]
	v_pk_add_f32 v[70:71], v[70:71], v[70:71] op_sel_hi:[0,1]
	v_add_f32_e32 v73, v8, v9
	v_add_f32_e32 v75, v10, v11
	v_mov_b32_e32 v72, v4
	v_mov_b32_e32 v74, v5
	v_mov_b32_e32 v70, v6
	v_mov_b32_e32 v68, v7
	v_pk_add_f32 v[72:73], v[72:73], v[74:75]
	v_pk_add_f32 v[68:69], v[70:71], v[68:69]
	s_mov_b64 s[8:9], 0x2000
	v_pk_add_f32 v[68:69], v[72:73], v[68:69]
	v_ashrrev_i32_e32 v97, 31, v96
	v_add_f32_e32 v68, v68, v69
	ds_bpermute_b32 v69, v196, v68
	s_add_i32 s47, s47, s28
	s_waitcnt lgkmcnt(0)
	v_add_f32_e32 v68, v68, v69
	ds_bpermute_b32 v69, v197, v68
	s_waitcnt lgkmcnt(0)
	v_add_f32_e32 v93, v68, v69
	v_fmamk_f32 v79, v93, 0xbb800000, v65
	v_fmamk_f32 v78, v93, 0xbb800000, v64
	v_fmamk_f32 v67, v93, 0xbb800000, v67
	v_fmac_f32_e32 v66, 0xbb800000, v93
	v_pk_mul_f32 v[64:65], v[66:67], v[66:67]
	v_pk_mul_f32 v[68:69], v[78:79], v[78:79]
	v_fmamk_f32 v77, v93, 0xbb800000, v61
	v_pk_mov_b32 v[70:71], v[68:69], v[64:65] op_sel:[1,0]
	v_mov_b32_e32 v69, v65
	v_fmamk_f32 v76, v93, 0xbb800000, v60
	v_fmamk_f32 v63, v93, 0xbb800000, v63
	v_fmac_f32_e32 v62, 0xbb800000, v93
	v_fmac_f32_e32 v44, 0xbb800000, v93
	v_pk_add_f32 v[64:65], v[70:71], v[68:69]
	v_pk_mul_f32 v[60:61], v[62:63], v[62:63]
	v_pk_mul_f32 v[68:69], v[76:77], v[76:77]
	v_fmamk_f32 v74, v93, 0xbb800000, v46
	v_fmamk_f32 v45, v93, 0xbb800000, v45
	v_mul_f32_e32 v46, v44, v44
	v_pk_mov_b32 v[70:71], v[68:69], v[60:61] op_sel:[1,0]
	v_mov_b32_e32 v69, v61
	v_fmamk_f32 v75, v93, 0xbb800000, v47
	v_pk_fma_f32 v[46:47], v[44:45], v[44:45], v[46:47] op_sel_hi:[1,1,0]
	v_pk_add_f32 v[60:61], v[70:71], v[68:69]
	v_mul_f32_e32 v46, v74, v74
	v_pk_add_f32 v[64:65], v[64:65], v[64:65] op_sel_hi:[0,1]
	v_pk_add_f32 v[60:61], v[60:61], v[60:61] op_sel_hi:[0,1]
	v_pk_fma_f32 v[68:69], v[74:75], v[74:75], v[46:47] op_sel_hi:[1,1,0]
	v_fmamk_f32 v73, v93, 0xbb800000, v51
	v_fmamk_f32 v72, v93, 0xbb800000, v50
	v_fmamk_f32 v49, v93, 0xbb800000, v49
	v_fmac_f32_e32 v48, 0xbb800000, v93
	v_mul_f32_e32 v46, v48, v48
	v_mul_f32_e32 v68, v49, v49
	v_mul_f32_e32 v64, v72, v72
	v_mul_f32_e32 v60, v73, v73
	v_pk_add_f32 v[46:47], v[46:47], v[68:69]
	v_pk_add_f32 v[50:51], v[64:65], v[60:61]
	v_fmamk_f32 v71, v93, 0xbb800000, v57
	v_pk_add_f32 v[46:47], v[46:47], v[50:51]
	v_fmamk_f32 v70, v93, 0xbb800000, v56
	v_fmamk_f32 v59, v93, 0xbb800000, v59
	v_fmac_f32_e32 v58, 0xbb800000, v93
	v_pk_add_f32 v[46:47], v[46:47], v[46:47] op_sel_hi:[0,1]
	v_pk_mul_f32 v[50:51], v[58:59], v[58:59]
	v_pk_mul_f32 v[56:57], v[70:71], v[70:71]
	v_fmac_f32_e32 v52, 0xbb800000, v93
	v_pk_mov_b32 v[60:61], v[56:57], v[50:51] op_sel:[1,0]
	v_mov_b32_e32 v57, v51
	v_fmamk_f32 v68, v93, 0xbb800000, v54
	v_fmamk_f32 v53, v93, 0xbb800000, v53
	v_mul_f32_e32 v46, v52, v52
	v_pk_add_f32 v[50:51], v[60:61], v[56:57]
	v_fmamk_f32 v69, v93, 0xbb800000, v55
	v_pk_fma_f32 v[54:55], v[52:53], v[52:53], v[46:47] op_sel_hi:[1,1,0]
	v_mul_f32_e32 v46, v68, v68
	v_pk_add_f32 v[50:51], v[50:51], v[50:51] op_sel_hi:[0,1]
	v_pk_fma_f32 v[56:57], v[68:69], v[68:69], v[46:47] op_sel_hi:[1,1,0]
	v_fmamk_f32 v65, v93, 0xbb800000, v39
	v_fmamk_f32 v64, v93, 0xbb800000, v38
; __device__ __forceinline__ float shx(float v, int lane, int m) { return __builtin_bit_cast(float, __builtin_amdgcn_ds_bpermute((lane ^ m) << 2, __builtin_bit_cast(int, v))); }
; __device__ __forceinline__ float siluf(float x) { return x * __builtin_amdgcn_rcpf(1.f + ex2(x * -1.44269504f)); }
; __device__ __forceinline__ void ret_out_item(const Params& p, int l, LAS unsigned char* lds, int item, int tid, int wave, int lane) {
;     ...
;     float vs = 0.f;
; #pragma unroll
;     for (int i = 0; i < 16; ++i) { o[i] = o[i] - mu; vs += (o[i][0] * o[i][0] + o[i][1] * o[i][1]) + (o[i][2] * o[i][2] + o[i][3] * o[i][3]); }
;     vs += shx(vs, lane, 16); vs += shx(vs, lane, 32);
;     const float rstd = 1.0f / sqrtf(vs * (1.f / 256.f) + EPS);
;     half_t* RA = (half_t*)(p.ws + WS_RA);
; #pragma unroll
;     for (int dvt = 0; dvt < 16; ++dvt) { const int col = h * 256 + dvt * 16 + 4 * g;
;         const f32x4 gw = *(const f32x4*)(p.gn_w + l * DM + col); const h4 rg = *(const h4*)(PR + (size_t)tok * NIN + C_RG + col);
;         h4 y;
; #pragma unroll
;         for (int e = 0; e < 4; ++e) y[e] = op16(o[dvt][e] * rstd * gw[e] * siluf((float)rg[e]), TAIL_BF16);
;         *(h4*)(RA + (size_t)tok * 4096 + col) = y; }
	v_fmamk_f32 v37, v93, 0xbb800000, v37
	v_fmac_f32_e32 v36, 0xbb800000, v93
	v_mul_f32_e32 v54, v36, v36
	v_mul_f32_e32 v56, v37, v37
	v_mul_f32_e32 v50, v64, v64
	v_mul_f32_e32 v46, v65, v65
	v_pk_add_f32 v[38:39], v[54:55], v[56:57]
	v_pk_add_f32 v[46:47], v[50:51], v[46:47]
	v_fmamk_f32 v61, v93, 0xbb800000, v41
	v_fmamk_f32 v60, v93, 0xbb800000, v40
	v_fmamk_f32 v43, v93, 0xbb800000, v43
	v_fmac_f32_e32 v42, 0xbb800000, v93
	v_fmac_f32_e32 v32, 0xbb800000, v93
	v_pk_add_f32 v[38:39], v[38:39], v[46:47]
	v_pk_mul_f32 v[40:41], v[42:43], v[42:43]
	v_pk_mul_f32 v[46:47], v[60:61], v[60:61]
	v_fmamk_f32 v56, v93, 0xbb800000, v34
	v_fmamk_f32 v33, v93, 0xbb800000, v33
	v_mul_f32_e32 v34, v32, v32
	v_pk_mov_b32 v[50:51], v[46:47], v[40:41] op_sel:[1,0]
	v_mov_b32_e32 v47, v41
	v_fmamk_f32 v57, v93, 0xbb800000, v35
	v_pk_fma_f32 v[34:35], v[32:33], v[32:33], v[34:35] op_sel_hi:[1,1,0]
	v_pk_add_f32 v[40:41], v[50:51], v[46:47]
	v_mul_f32_e32 v34, v56, v56
	v_pk_add_f32 v[38:39], v[38:39], v[38:39] op_sel_hi:[0,1]
	v_pk_add_f32 v[40:41], v[40:41], v[40:41] op_sel_hi:[0,1]
	v_pk_fma_f32 v[46:47], v[56:57], v[56:57], v[34:35] op_sel_hi:[1,1,0]
	v_fmamk_f32 v55, v93, 0xbb800000, v31
	v_fmamk_f32 v54, v93, 0xbb800000, v30
	v_fmamk_f32 v29, v93, 0xbb800000, v29
	v_fmac_f32_e32 v28, 0xbb800000, v93
	v_mul_f32_e32 v34, v28, v28
	v_mul_f32_e32 v46, v29, v29
	v_mul_f32_e32 v40, v54, v54
	v_mul_f32_e32 v38, v55, v55
	v_pk_add_f32 v[30:31], v[34:35], v[46:47]
	v_pk_add_f32 v[34:35], v[40:41], v[38:39]
	v_fmamk_f32 v51, v93, 0xbb800000, v21
	v_fmamk_f32 v50, v93, 0xbb800000, v20
	v_fmamk_f32 v23, v93, 0xbb800000, v23
	v_fmac_f32_e32 v22, 0xbb800000, v93
	v_pk_add_f32 v[30:31], v[30:31], v[34:35]
	v_pk_mul_f32 v[20:21], v[22:23], v[22:23]
	v_pk_mul_f32 v[34:35], v[50:51], v[50:51]
	v_fmac_f32_e32 v24, 0xbb800000, v93
	v_pk_mov_b32 v[38:39], v[34:35], v[20:21] op_sel:[1,0]
	v_mov_b32_e32 v35, v21
	v_pk_add_f32 v[20:21], v[38:39], v[34:35]
	v_fmamk_f32 v46, v93, 0xbb800000, v26
	v_pk_add_f32 v[20:21], v[20:21], v[20:21] op_sel_hi:[0,1]
	v_fmamk_f32 v25, v93, 0xbb800000, v25
	v_mul_f32_e32 v20, v24, v24
	v_fmamk_f32 v47, v93, 0xbb800000, v27
	v_pk_fma_f32 v[26:27], v[24:25], v[24:25], v[20:21] op_sel_hi:[1,1,0]
	v_mul_f32_e32 v20, v46, v46
	v_pk_add_f32 v[30:31], v[30:31], v[30:31] op_sel_hi:[0,1]
	v_pk_fma_f32 v[34:35], v[46:47], v[46:47], v[20:21] op_sel_hi:[1,1,0]
	v_fmamk_f32 v41, v93, 0xbb800000, v19
	v_fmamk_f32 v40, v93, 0xbb800000, v18
	v_fmamk_f32 v17, v93, 0xbb800000, v17
	v_fmac_f32_e32 v16, 0xbb800000, v93
	v_mul_f32_e32 v26, v16, v16
	v_mul_f32_e32 v34, v17, v17
	v_mul_f32_e32 v20, v40, v40
	v_mul_f32_e32 v30, v41, v41
	v_pk_add_f32 v[18:19], v[26:27], v[34:35]
	v_pk_add_f32 v[20:21], v[20:21], v[30:31]
	v_lshl_add_u64 v[30:31], v[98:99], 0, s[8:9]
	v_pk_add_f32 v[18:19], v[18:19], v[20:21]
	v_mov_b32_e32 v39, v3
	v_pk_add_f32 v[26:27], v[18:19], v[18:19] op_sel_hi:[0,1]
	v_or_b32_e32 v26, s20, v138
	v_lshlrev_b32_e32 v38, 1, v26
	v_fmamk_f32 v35, v93, 0xbb800000, v13
	v_fmamk_f32 v34, v93, 0xbb800000, v12
	v_fmamk_f32 v15, v93, 0xbb800000, v15
	v_fmac_f32_e32 v14, 0xbb800000, v93
	v_lshl_add_u64 v[18:19], v[30:31], 0, v[38:39]
	v_pk_mul_f32 v[12:13], v[14:15], v[14:15]
	v_lshlrev_b32_e32 v100, 2, v26
	global_load_dwordx2 v[240:241], v[18:19], off
	global_load_dwordx2 v[242:243], v[18:19], off offset:32
	global_load_dwordx2 v[244:245], v[18:19], off offset:64
	global_load_dwordx2 v[246:247], v[18:19], off offset:96
	global_load_dwordx2 v[248:249], v[18:19], off offset:128
	global_load_dwordx2 v[106:107], v[18:19], off offset:160
	global_load_dwordx2 v[108:109], v[18:19], off offset:192
	global_load_dwordx2 v[110:111], v[18:19], off offset:224
	global_load_dwordx2 v[112:113], v[18:19], off offset:256
	global_load_dwordx2 v[114:115], v[18:19], off offset:288
	global_load_dwordx2 v[116:117], v[18:19], off offset:320
	global_load_dwordx2 v[118:119], v[18:19], off offset:352
	global_load_dwordx2 v[120:121], v[18:19], off offset:384
	global_load_dwordx2 v[122:123], v[18:19], off offset:416
	global_load_dwordx2 v[206:207], v[18:19], off offset:448
	global_load_dwordx2 v[102:103], v[18:19], off offset:480
	global_load_dwordx4 v[208:211], v100, s[42:43]
	global_load_dwordx4 v[212:215], v100, s[42:43] offset:64
	global_load_dwordx4 v[216:219], v100, s[42:43] offset:128
	global_load_dwordx4 v[220:223], v100, s[42:43] offset:192
	global_load_dwordx4 v[224:227], v100, s[42:43] offset:256
	global_load_dwordx4 v[228:231], v100, s[42:43] offset:320
	global_load_dwordx4 v[232:235], v100, s[42:43] offset:384
	global_load_dwordx4 v[236:239], v100, s[42:43] offset:448
	s_waitcnt vmcnt(7)
	v_mov_b32_e32 v80, v240
	v_mov_b32_e32 v81, v241
	v_pk_mul_f32 v[18:19], v[34:35], v[34:35]
	v_fmac_f32_e32 v8, 0xbb800000, v93
	v_pk_mov_b32 v[20:21], v[18:19], v[12:13] op_sel:[1,0]
	v_mov_b32_e32 v19, v13
	v_pk_add_f32 v[12:13], v[20:21], v[18:19]
	v_fmamk_f32 v18, v93, 0xbb800000, v10
	v_fmamk_f32 v9, v93, 0xbb800000, v9
	v_mul_f32_e32 v10, v8, v8
	v_fmamk_f32 v19, v93, 0xbb800000, v11
	v_pk_fma_f32 v[84:85], v[8:9], v[8:9], v[10:11] op_sel_hi:[1,1,0]
	v_mul_f32_e32 v10, v18, v18
	v_lshlrev_b32_e32 v21, 2, v26
	v_pk_add_f32 v[82:83], v[12:13], v[12:13] op_sel_hi:[0,1]
	v_pk_fma_f32 v[86:87], v[18:19], v[18:19], v[10:11] op_sel_hi:[1,1,0]
	s_waitcnt vmcnt(7)
; __device__ __forceinline__ float siluf(float x) { return x * __builtin_amdgcn_rcpf(1.f + ex2(x * -1.44269504f)); }
; __device__ __forceinline__ void ret_out_item(const Params& p, int l, LAS unsigned char* lds, int item, int tid, int wave, int lane) {
;     ...
;     const float rstd = 1.0f / sqrtf(vs * (1.f / 256.f) + EPS);
;     half_t* RA = (half_t*)(p.ws + WS_RA);
; #pragma unroll
;     for (int dvt = 0; dvt < 16; ++dvt) { const int col = h * 256 + dvt * 16 + 4 * g;
;         const f32x4 gw = *(const f32x4*)(p.gn_w + l * DM + col); const h4 rg = *(const h4*)(PR + (size_t)tok * NIN + C_RG + col);
;         h4 y;
; #pragma unroll
;         for (int e = 0; e < 4; ++e) y[e] = op16(o[dvt][e] * rstd * gw[e] * siluf((float)rg[e]), TAIL_BF16);
;         *(h4*)(RA + (size_t)tok * 4096 + col) = y; }
	v_mov_b32_e32 v10, v208
	v_mov_b32_e32 v11, v209
	v_mov_b32_e32 v12, v210
	v_mov_b32_e32 v13, v211
	global_load_dwordx4 v[208:211], v100, s[42:43] offset:512
	v_fmamk_f32 v7, v93, 0xbb800000, v7
	v_fmamk_f32 v6, v93, 0xbb800000, v6
	v_fmamk_f32 v5, v93, 0xbb800000, v5
	v_fmac_f32_e32 v4, 0xbb800000, v93
	v_mul_f32_e32 v84, v4, v4
	v_mul_f32_e32 v86, v5, v5
	v_mul_f32_e32 v82, v6, v6
	v_mul_f32_e32 v26, v7, v7
	v_pk_add_f32 v[84:85], v[84:85], v[86:87]
	v_pk_add_f32 v[26:27], v[82:83], v[26:27]
	s_mov_b32 s8, 0xf800000
	v_pk_add_f32 v[26:27], v[84:85], v[26:27]
	s_nop 0
	v_add_f32_e32 v20, v26, v27
	ds_bpermute_b32 v26, v196, v20
	s_waitcnt lgkmcnt(0)
	v_add_f32_e32 v20, v20, v26
	ds_bpermute_b32 v26, v197, v20
	s_waitcnt lgkmcnt(0)
	v_add_f32_e32 v20, v20, v26
	v_fmamk_f32 v20, v20, 0x3b800000, v181
	v_mul_f32_e32 v26, 0x4f800000, v20
	v_cmp_gt_f32_e64 s[8:9], s8, v20
	s_nop 1
	v_cndmask_b32_e64 v20, v20, v26, s[8:9]
	v_sqrt_f32_e32 v26, v20
	s_nop 0
	v_add_u32_e32 v27, -1, v26
	v_fma_f32 v82, -v27, v26, v20
	v_cmp_ge_f32_e32 vcc, 0, v82
	v_add_u32_e32 v82, 1, v26
	s_nop 0
	v_cndmask_b32_e32 v27, v26, v27, vcc
	v_fma_f32 v26, -v82, v26, v20
	v_cmp_lt_f32_e32 vcc, 0, v26
	s_nop 1
	v_cndmask_b32_e32 v26, v27, v82, vcc
	v_mul_f32_e32 v27, 0x37800000, v26
	v_cndmask_b32_e64 v26, v26, v27, s[8:9]
	v_cmp_class_f32_e32 vcc, v20, v182
	s_nop 1
	v_cndmask_b32_e32 v20, v26, v20, vcc
	v_div_scale_f32 v26, s[8:9], v20, v20, 1.0
	v_rcp_f32_e32 v27, v26
	v_readlane_b32 s8, v253, 42
	v_readlane_b32 s9, v253, 43
	v_fma_f32 v82, -v26, v27, 1.0
	v_fmac_f32_e32 v27, v82, v27
	v_div_scale_f32 v82, vcc, 1.0, v20, 1.0
	v_mul_f32_e32 v83, v82, v27
	v_fma_f32 v84, -v26, v83, v82
	v_fmac_f32_e32 v83, v84, v27
	v_fma_f32 v26, -v26, v83, v82
	v_div_fmas_f32 v84, v26, v27, v83
	v_div_fixup_f32 v20, v84, v20, 1.0
	v_pk_mul_f32 v[66:67], v[66:67], v[20:21] op_sel_hi:[1,0]
	v_or_b32_e32 v26, 32, v38
	v_mov_b32_e32 v27, v3
	v_lshl_add_u64 v[26:27], v[30:31], 0, v[26:27]
	v_mov_b32_e32 v82, v242
	v_mov_b32_e32 v83, v243
	v_pk_mul_f32 v[78:79], v[78:79], v[20:21] op_sel_hi:[1,0]
	v_lshlrev_b64 v[84:85], 13, v[96:97]
	v_lshl_add_u64 v[84:85], s[8:9], 0, v[84:85]
	v_pk_mul_f32 v[76:77], v[76:77], v[20:21] op_sel_hi:[1,0]
	v_pk_mul_f32 v[62:63], v[62:63], v[20:21] op_sel_hi:[1,0]
	s_nop 0
	v_pk_mul_f32 v[12:13], v[12:13], v[66:67]
	v_or_b32_e32 v66, 64, v38
	v_mov_b32_e32 v67, v3
	v_lshl_add_u64 v[66:67], v[30:31], 0, v[66:67]
	v_mov_b32_e32 v66, v244
	v_mov_b32_e32 v67, v245
	v_cvt_f32_f16_e32 v26, v80
	v_cvt_f32_f16_sdwa v27, v80 dst_sel:DWORD dst_unused:UNUSED_PAD src0_sel:WORD_1
	v_pk_mul_f32 v[10:11], v[10:11], v[78:79]
	v_pk_mul_f32 v[44:45], v[44:45], v[20:21] op_sel_hi:[1,0]
	v_mul_f32_e32 v80, 0xbfb8aa3b, v26
	v_exp_f32_e32 v80, v80
	v_mul_f32_e32 v86, 0xbfb8aa3b, v27
	v_exp_f32_e32 v87, v86
	v_pk_mul_f32 v[74:75], v[74:75], v[20:21] op_sel_hi:[1,0]
	v_add_f32_e32 v80, 1.0, v80
	v_rcp_f32_e32 v86, v80
	v_add_f32_e32 v80, 1.0, v87
	v_rcp_f32_e32 v87, v80
	v_cvt_f32_f16_e32 v80, v81
	v_cvt_f32_f16_sdwa v81, v81 dst_sel:DWORD dst_unused:UNUSED_PAD src0_sel:WORD_1
	v_pk_mul_f32 v[48:49], v[48:49], v[20:21] op_sel_hi:[1,0]
	v_pk_mul_f32 v[26:27], v[86:87], v[26:27]
	v_mul_f32_e32 v78, 0xbfb8aa3b, v80
	v_mul_f32_e32 v79, 0xbfb8aa3b, v81
	v_exp_f32_e32 v78, v78
	v_exp_f32_e32 v79, v79
	v_pk_mul_f32 v[10:11], v[26:27], v[10:11]
	v_pk_mul_f32 v[70:71], v[70:71], v[20:21] op_sel_hi:[1,0]
	v_add_f32_e32 v26, 1.0, v78
	v_add_f32_e32 v27, 1.0, v79
	v_rcp_f32_e32 v26, v26
	v_rcp_f32_e32 v27, v27
	v_cvt_pk_bf16_f32 v10, v10, v11
	v_pk_mul_f32 v[58:59], v[58:59], v[20:21] op_sel_hi:[1,0]
	v_pk_mul_f32 v[52:53], v[52:53], v[20:21] op_sel_hi:[1,0]
	v_pk_mul_f32 v[26:27], v[26:27], v[80:81]
	v_pk_mul_f32 v[36:37], v[36:37], v[20:21] op_sel_hi:[1,0]
	v_pk_mul_f32 v[12:13], v[26:27], v[12:13]
	v_lshl_add_u64 v[26:27], v[84:85], 0, v[38:39]
	v_cvt_pk_bf16_f32 v11, v12, v13
	global_store_dwordx2 v[26:27], v[10:11], off
	s_waitcnt vmcnt(7)
	v_mov_b32_e32 v10, v212
	v_mov_b32_e32 v11, v213
	v_mov_b32_e32 v12, v214
	v_mov_b32_e32 v13, v215
	global_load_dwordx4 v[212:215], v100, s[42:43] offset:576
	v_pk_mul_f32 v[42:43], v[42:43], v[20:21] op_sel_hi:[1,0]
	v_pk_mul_f32 v[32:33], v[32:33], v[20:21] op_sel_hi:[1,0]
	v_pk_mul_f32 v[28:29], v[28:29], v[20:21] op_sel_hi:[1,0]
	v_pk_mul_f32 v[22:23], v[22:23], v[20:21] op_sel_hi:[1,0]
	v_pk_mul_f32 v[24:25], v[24:25], v[20:21] op_sel_hi:[1,0]
	v_pk_mul_f32 v[16:17], v[16:17], v[20:21] op_sel_hi:[1,0]
	v_pk_mul_f32 v[14:15], v[14:15], v[20:21] op_sel_hi:[1,0]
	v_pk_mul_f32 v[8:9], v[8:9], v[20:21] op_sel_hi:[1,0]
	v_pk_mul_f32 v[18:19], v[18:19], v[20:21] op_sel_hi:[1,0]
	v_readlane_b32 s8, v253, 63
	v_pk_mul_f32 v[4:5], v[4:5], v[20:21] op_sel_hi:[1,0]
	v_pk_mul_f32 v[6:7], v[6:7], v[20:21] op_sel_hi:[1,0]
	s_add_i32 s46, s46, s8
	v_readlane_b32 s8, v251, 3
	v_readlane_b32 s9, v251, 4
	s_cmpk_gt_i32 s47, 0x1ff
	s_nop 0
	v_cvt_f32_f16_e32 v78, v82
	v_cvt_f32_f16_sdwa v79, v82 dst_sel:DWORD dst_unused:UNUSED_PAD src0_sel:WORD_1
	v_cvt_f32_f16_e32 v82, v83
	v_cvt_f32_f16_sdwa v83, v83 dst_sel:DWORD dst_unused:UNUSED_PAD src0_sel:WORD_1
	v_mul_f32_e32 v39, 0xbfb8aa3b, v78
	v_exp_f32_e32 v39, v39
	v_mul_f32_e32 v80, 0xbfb8aa3b, v79
	v_exp_f32_e32 v81, v80
	v_lshl_add_u64 v[90:91], v[90:91], 0, s[8:9]
	v_add_f32_e32 v39, 1.0, v39
	v_rcp_f32_e32 v80, v39
	v_add_f32_e32 v39, 1.0, v81
	v_rcp_f32_e32 v81, v39
	v_mul_f32_e32 v39, 0xbfb8aa3b, v82
	v_exp_f32_e32 v39, v39
	s_nop 0
	v_pk_mul_f32 v[10:11], v[10:11], v[76:77]
	v_pk_mul_f32 v[76:77], v[80:81], v[78:79]
	v_mul_f32_e32 v78, 0xbfb8aa3b, v83
	v_exp_f32_e32 v78, v78
	v_add_f32_e32 v39, 1.0, v39
	v_pk_mul_f32 v[10:11], v[76:77], v[10:11]
	v_rcp_f32_e32 v76, v39
	v_add_f32_e32 v39, 1.0, v78
	v_rcp_f32_e32 v77, v39
	v_pk_mul_f32 v[12:13], v[12:13], v[62:63]
	v_cvt_pk_bf16_f32 v10, v10, v11
	v_pk_mul_f32 v[62:63], v[76:77], v[82:83]
	s_nop 0
	v_pk_mul_f32 v[12:13], v[62:63], v[12:13]
	v_cvt_f32_f16_e32 v76, v66
	v_cvt_pk_bf16_f32 v11, v12, v13
	global_store_dwordx2 v[26:27], v[10:11], off offset:32
	s_waitcnt vmcnt(7)
; __device__ __forceinline__ float siluf(float x) { return x * __builtin_amdgcn_rcpf(1.f + ex2(x * -1.44269504f)); }
; __device__ __forceinline__ void ret_out_item(const Params& p, int l, LAS unsigned char* lds, int item, int tid, int wave, int lane) {
;     ...
; #pragma unroll
;     for (int dvt = 0; dvt < 16; ++dvt) { const int col = h * 256 + dvt * 16 + 4 * g;
;         const f32x4 gw = *(const f32x4*)(p.gn_w + l * DM + col); const h4 rg = *(const h4*)(PR + (size_t)tok * NIN + C_RG + col);
;         h4 y;
; #pragma unroll
;         for (int e = 0; e < 4; ++e) y[e] = op16(o[dvt][e] * rstd * gw[e] * siluf((float)rg[e]), TAIL_BF16);
;         *(h4*)(RA + (size_t)tok * 4096 + col) = y; }
	v_mov_b32_e32 v10, v216
	v_mov_b32_e32 v11, v217
	v_mov_b32_e32 v12, v218
	v_mov_b32_e32 v13, v219
	global_load_dwordx4 v[216:219], v100, s[42:43] offset:640
	v_cvt_f32_f16_sdwa v77, v66 dst_sel:DWORD dst_unused:UNUSED_PAD src0_sel:WORD_1
	v_mul_f32_e32 v39, 0xbfb8aa3b, v76
	v_exp_f32_e32 v39, v39
	v_or_b32_e32 v62, 0x60, v38
	v_mul_f32_e32 v66, 0xbfb8aa3b, v77
	v_exp_f32_e32 v66, v66
	v_add_f32_e32 v39, 1.0, v39
	v_rcp_f32_e32 v78, v39
	v_mov_b32_e32 v63, v3
	v_add_f32_e32 v39, 1.0, v66
	v_cvt_f32_f16_e32 v66, v67
	v_rcp_f32_e32 v79, v39
	v_cvt_f32_f16_sdwa v67, v67 dst_sel:DWORD dst_unused:UNUSED_PAD src0_sel:WORD_1
	v_lshl_add_u64 v[62:63], v[30:31], 0, v[62:63]
	v_mul_f32_e32 v39, 0xbfb8aa3b, v66
	v_exp_f32_e32 v39, v39
	v_mov_b32_e32 v62, v246
	v_mov_b32_e32 v63, v247
	v_add_f32_e32 v39, 1.0, v39
	s_nop 0
	v_pk_mul_f32 v[10:11], v[10:11], v[44:45]
	v_pk_mul_f32 v[44:45], v[78:79], v[76:77]
	v_mul_f32_e32 v76, 0xbfb8aa3b, v67
	v_exp_f32_e32 v76, v76
	v_pk_mul_f32 v[10:11], v[44:45], v[10:11]
	v_rcp_f32_e32 v44, v39
	v_pk_mul_f32 v[12:13], v[12:13], v[74:75]
	v_add_f32_e32 v39, 1.0, v76
	v_rcp_f32_e32 v45, v39
	v_cvt_pk_bf16_f32 v10, v10, v11
	v_pk_mul_f32 v[44:45], v[44:45], v[66:67]
	s_nop 0
	v_pk_mul_f32 v[12:13], v[44:45], v[12:13]
	s_nop 0
	v_cvt_pk_bf16_f32 v11, v12, v13
	global_store_dwordx2 v[26:27], v[10:11], off offset:64
	s_waitcnt vmcnt(7)
	v_mov_b32_e32 v10, v220
	v_mov_b32_e32 v11, v221
	v_mov_b32_e32 v12, v222
	v_mov_b32_e32 v13, v223
	global_load_dwordx4 v[220:223], v100, s[42:43] offset:704
	s_nop 0
	v_pk_mul_f32 v[10:11], v[10:11], v[48:49]
	v_or_b32_e32 v48, 0x80, v38
	v_mov_b32_e32 v49, v3
	v_lshl_add_u64 v[48:49], v[30:31], 0, v[48:49]
	v_mov_b32_e32 v48, v248
	v_mov_b32_e32 v49, v249
	v_cvt_f32_f16_e32 v44, v62
	v_cvt_f32_f16_sdwa v45, v62 dst_sel:DWORD dst_unused:UNUSED_PAD src0_sel:WORD_1
	v_mul_f32_e32 v39, 0xbfb8aa3b, v44
	v_exp_f32_e32 v39, v39
	v_mul_f32_e32 v62, 0xbfb8aa3b, v45
	v_exp_f32_e32 v62, v62
	v_add_f32_e32 v39, 1.0, v39
	v_rcp_f32_e32 v66, v39
	v_add_f32_e32 v39, 1.0, v62
	v_cvt_f32_f16_e32 v62, v63
	v_rcp_f32_e32 v67, v39
	v_cvt_f32_f16_sdwa v63, v63 dst_sel:DWORD dst_unused:UNUSED_PAD src0_sel:WORD_1
	v_mul_f32_e32 v39, 0xbfb8aa3b, v62
	v_pk_mul_f32 v[44:45], v[66:67], v[44:45]
	v_exp_f32_e32 v39, v39
	v_mul_f32_e32 v66, 0xbfb8aa3b, v63
	v_exp_f32_e32 v66, v66
	v_pk_mul_f32 v[10:11], v[44:45], v[10:11]
	v_add_f32_e32 v39, 1.0, v39
	v_rcp_f32_e32 v44, v39
	v_add_f32_e32 v39, 1.0, v66
	v_rcp_f32_e32 v45, v39
	v_pk_mul_f32 v[66:67], v[72:73], v[20:21] op_sel_hi:[1,0]
	v_cvt_pk_bf16_f32 v10, v10, v11
	v_pk_mul_f32 v[12:13], v[12:13], v[66:67]
	v_pk_mul_f32 v[44:45], v[44:45], v[62:63]
	s_nop 0
	v_pk_mul_f32 v[12:13], v[44:45], v[12:13]
	v_or_b32_e32 v44, 0xa0, v38
	v_cvt_pk_bf16_f32 v11, v12, v13
	global_store_dwordx2 v[26:27], v[10:11], off offset:96
	s_waitcnt vmcnt(7)
	v_mov_b32_e32 v10, v224
	v_mov_b32_e32 v11, v225
	v_mov_b32_e32 v12, v226
	v_mov_b32_e32 v13, v227
	global_load_dwordx4 v[224:227], v100, s[42:43] offset:768
	v_mov_b32_e32 v45, v3
	v_lshl_add_u64 v[44:45], v[30:31], 0, v[44:45]
	v_mov_b32_e32 v44, v106
	v_mov_b32_e32 v45, v107
	s_nop 0
	v_cvt_f32_f16_e32 v62, v48
	v_cvt_f32_f16_sdwa v63, v48 dst_sel:DWORD dst_unused:UNUSED_PAD src0_sel:WORD_1
	v_mul_f32_e32 v39, 0xbfb8aa3b, v62
	v_exp_f32_e32 v39, v39
	v_mul_f32_e32 v48, 0xbfb8aa3b, v63
	v_exp_f32_e32 v48, v48
	v_add_f32_e32 v39, 1.0, v39
	v_rcp_f32_e32 v66, v39
	v_add_f32_e32 v39, 1.0, v48
	v_cvt_f32_f16_e32 v48, v49
	v_rcp_f32_e32 v67, v39
	v_cvt_f32_f16_sdwa v49, v49 dst_sel:DWORD dst_unused:UNUSED_PAD src0_sel:WORD_1
	v_mul_f32_e32 v39, 0xbfb8aa3b, v48
	v_pk_mul_f32 v[62:63], v[66:67], v[62:63]
	v_exp_f32_e32 v39, v39
	v_mul_f32_e32 v66, 0xbfb8aa3b, v49
	v_exp_f32_e32 v66, v66
	v_add_f32_e32 v39, 1.0, v39
	s_nop 0
	v_pk_mul_f32 v[10:11], v[10:11], v[70:71]
	s_nop 0
	v_pk_mul_f32 v[10:11], v[62:63], v[10:11]
	v_rcp_f32_e32 v62, v39
	v_add_f32_e32 v39, 1.0, v66
	v_rcp_f32_e32 v63, v39
	v_pk_mul_f32 v[12:13], v[12:13], v[58:59]
	v_cvt_pk_bf16_f32 v10, v10, v11
	s_nop 0
	v_cvt_f32_f16_e32 v58, v44
	v_pk_mul_f32 v[48:49], v[62:63], v[48:49]
	v_cvt_f32_f16_sdwa v59, v44 dst_sel:DWORD dst_unused:UNUSED_PAD src0_sel:WORD_1
	v_pk_mul_f32 v[12:13], v[48:49], v[12:13]
	v_cvt_f32_f16_e32 v44, v45
	v_cvt_pk_bf16_f32 v11, v12, v13
	global_store_dwordx2 v[26:27], v[10:11], off offset:128
	s_waitcnt vmcnt(7)
	v_mov_b32_e32 v10, v228
	v_mov_b32_e32 v11, v229
	v_mov_b32_e32 v12, v230
	v_mov_b32_e32 v13, v231
	global_load_dwordx4 v[228:231], v100, s[42:43] offset:832
	v_cvt_f32_f16_sdwa v45, v45 dst_sel:DWORD dst_unused:UNUSED_PAD src0_sel:WORD_1
	v_mov_b32_e32 v49, v3
	v_or_b32_e32 v48, 0xc0, v38
	v_lshl_add_u64 v[48:49], v[30:31], 0, v[48:49]
	v_mov_b32_e32 v48, v108
	v_mov_b32_e32 v49, v109
	v_mul_f32_e32 v39, 0xbfb8aa3b, v58
	v_mul_f32_e32 v62, 0xbfb8aa3b, v59
	v_mul_f32_e32 v63, 0xbfb8aa3b, v44
	v_mul_f32_e32 v66, 0xbfb8aa3b, v45
	v_exp_f32_e32 v39, v39
	v_exp_f32_e32 v62, v62
	v_exp_f32_e32 v63, v63
	v_exp_f32_e32 v66, v66
	v_add_f32_e32 v39, 1.0, v39
	v_add_f32_e32 v67, 1.0, v62
	v_add_f32_e32 v70, 1.0, v63
	v_add_f32_e32 v71, 1.0, v66
	v_rcp_f32_e32 v62, v39
	v_rcp_f32_e32 v63, v67
	v_rcp_f32_e32 v66, v70
	v_rcp_f32_e32 v67, v71
	v_pk_mul_f32 v[58:59], v[62:63], v[58:59]
	v_pk_mul_f32 v[62:63], v[68:69], v[20:21] op_sel_hi:[1,0]
	v_pk_mul_f32 v[44:45], v[66:67], v[44:45]
	s_nop 0
	v_pk_mul_f32 v[10:11], v[10:11], v[52:53]
	v_pk_mul_f32 v[12:13], v[12:13], v[62:63]
	v_pk_mul_f32 v[10:11], v[58:59], v[10:11]
	v_pk_mul_f32 v[12:13], v[44:45], v[12:13]
	v_cvt_pk_bf16_f32 v10, v10, v11
	v_cvt_pk_bf16_f32 v11, v12, v13
	global_store_dwordx2 v[26:27], v[10:11], off offset:160
	s_waitcnt vmcnt(7)
; __device__ __forceinline__ float siluf(float x) { return x * __builtin_amdgcn_rcpf(1.f + ex2(x * -1.44269504f)); }
; __device__ __forceinline__ void ret_out_item(const Params& p, int l, LAS unsigned char* lds, int item, int tid, int wave, int lane) {
;     ...
; #pragma unroll
;     for (int dvt = 0; dvt < 16; ++dvt) { const int col = h * 256 + dvt * 16 + 4 * g;
;         const f32x4 gw = *(const f32x4*)(p.gn_w + l * DM + col); const h4 rg = *(const h4*)(PR + (size_t)tok * NIN + C_RG + col);
;         h4 y;
; #pragma unroll
;         for (int e = 0; e < 4; ++e) y[e] = op16(o[dvt][e] * rstd * gw[e] * siluf((float)rg[e]), TAIL_BF16);
;         *(h4*)(RA + (size_t)tok * 4096 + col) = y; }
	v_mov_b32_e32 v10, v232
	v_mov_b32_e32 v11, v233
	v_mov_b32_e32 v12, v234
	v_mov_b32_e32 v13, v235
	global_load_dwordx4 v[232:235], v100, s[42:43] offset:896
	v_mov_b32_e32 v45, v3
	v_or_b32_e32 v44, 0xe0, v38
	v_lshl_add_u64 v[44:45], v[30:31], 0, v[44:45]
	v_mov_b32_e32 v44, v110
	v_mov_b32_e32 v45, v111
	s_nop 0
	v_cvt_f32_f16_e32 v52, v48
	v_cvt_f32_f16_sdwa v53, v48 dst_sel:DWORD dst_unused:UNUSED_PAD src0_sel:WORD_1
	v_cvt_f32_f16_e32 v48, v49
	v_cvt_f32_f16_sdwa v49, v49 dst_sel:DWORD dst_unused:UNUSED_PAD src0_sel:WORD_1
	v_mul_f32_e32 v39, 0xbfb8aa3b, v52
	v_mul_f32_e32 v58, 0xbfb8aa3b, v53
	v_mul_f32_e32 v59, 0xbfb8aa3b, v48
	v_mul_f32_e32 v62, 0xbfb8aa3b, v49
	v_exp_f32_e32 v39, v39
	v_exp_f32_e32 v58, v58
	v_exp_f32_e32 v59, v59
	v_exp_f32_e32 v62, v62
	v_add_f32_e32 v39, 1.0, v39
	v_add_f32_e32 v63, 1.0, v58
	v_add_f32_e32 v66, 1.0, v59
	v_add_f32_e32 v67, 1.0, v62
	v_rcp_f32_e32 v58, v39
	v_rcp_f32_e32 v59, v63
	v_rcp_f32_e32 v62, v66
	v_rcp_f32_e32 v63, v67
	v_pk_mul_f32 v[52:53], v[58:59], v[52:53]
	v_pk_mul_f32 v[58:59], v[64:65], v[20:21] op_sel_hi:[1,0]
	v_pk_mul_f32 v[48:49], v[62:63], v[48:49]
	s_nop 0
	v_pk_mul_f32 v[10:11], v[10:11], v[36:37]
	v_pk_mul_f32 v[12:13], v[12:13], v[58:59]
	v_pk_mul_f32 v[10:11], v[52:53], v[10:11]
	v_pk_mul_f32 v[12:13], v[48:49], v[12:13]
	v_cvt_pk_bf16_f32 v10, v10, v11
	v_cvt_pk_bf16_f32 v11, v12, v13
	global_store_dwordx2 v[26:27], v[10:11], off offset:192
	s_waitcnt vmcnt(7)
	v_mov_b32_e32 v10, v236
	v_mov_b32_e32 v11, v237
	v_mov_b32_e32 v12, v238
	v_mov_b32_e32 v13, v239
	global_load_dwordx4 v[236:239], v100, s[42:43] offset:960
	s_nop 0
	v_cvt_f32_f16_e32 v48, v44
	v_cvt_f32_f16_sdwa v49, v44 dst_sel:DWORD dst_unused:UNUSED_PAD src0_sel:WORD_1
	v_cvt_f32_f16_e32 v44, v45
	v_cvt_f32_f16_sdwa v45, v45 dst_sel:DWORD dst_unused:UNUSED_PAD src0_sel:WORD_1
	v_mul_f32_e32 v39, 0xbfb8aa3b, v48
	v_mul_f32_e32 v52, 0xbfb8aa3b, v49
	v_mul_f32_e32 v53, 0xbfb8aa3b, v44
	v_mul_f32_e32 v58, 0xbfb8aa3b, v45
	v_exp_f32_e32 v39, v39
	v_exp_f32_e32 v52, v52
	v_exp_f32_e32 v53, v53
	v_exp_f32_e32 v58, v58
	v_add_f32_e32 v39, 1.0, v39
	v_add_f32_e32 v59, 1.0, v52
	v_add_f32_e32 v62, 1.0, v53
	v_add_f32_e32 v63, 1.0, v58
	v_rcp_f32_e32 v52, v39
	v_rcp_f32_e32 v53, v59
	v_rcp_f32_e32 v58, v62
	v_rcp_f32_e32 v59, v63
	v_mov_b32_e32 v37, v3
	v_pk_mul_f32 v[48:49], v[52:53], v[48:49]
	v_pk_mul_f32 v[52:53], v[60:61], v[20:21] op_sel_hi:[1,0]
	v_pk_mul_f32 v[44:45], v[58:59], v[44:45]
	v_or_b32_e32 v36, 0x100, v38
	v_lshl_add_u64 v[36:37], v[30:31], 0, v[36:37]
	v_mov_b32_e32 v36, v112
	v_mov_b32_e32 v37, v113
	s_nop 0
	v_pk_mul_f32 v[10:11], v[10:11], v[52:53]
	v_pk_mul_f32 v[12:13], v[12:13], v[42:43]
	v_pk_mul_f32 v[10:11], v[48:49], v[10:11]
	v_pk_mul_f32 v[12:13], v[44:45], v[12:13]
	v_cvt_pk_bf16_f32 v10, v10, v11
	v_cvt_pk_bf16_f32 v11, v12, v13
	global_store_dwordx2 v[26:27], v[10:11], off offset:224
	s_waitcnt vmcnt(7)
	v_mov_b32_e32 v10, v208
	v_mov_b32_e32 v11, v209
	v_mov_b32_e32 v12, v210
	v_mov_b32_e32 v13, v211
	v_mov_b32_e32 v43, v3
	v_or_b32_e32 v42, 0x120, v38
	v_lshl_add_u64 v[42:43], v[30:31], 0, v[42:43]
	v_mov_b32_e32 v42, v114
	v_mov_b32_e32 v43, v115
	s_nop 0
	v_pk_mul_f32 v[10:11], v[10:11], v[32:33]
	v_mov_b32_e32 v33, v3
	v_or_b32_e32 v32, 0x140, v38
	v_lshl_add_u64 v[32:33], v[30:31], 0, v[32:33]
	v_mov_b32_e32 v32, v116
	v_mov_b32_e32 v33, v117
	v_cvt_f32_f16_e32 v44, v36
	v_cvt_f32_f16_sdwa v45, v36 dst_sel:DWORD dst_unused:UNUSED_PAD src0_sel:WORD_1
	v_cvt_f32_f16_e32 v36, v37
	v_cvt_f32_f16_sdwa v37, v37 dst_sel:DWORD dst_unused:UNUSED_PAD src0_sel:WORD_1
	v_mul_f32_e32 v39, 0xbfb8aa3b, v44
	v_mul_f32_e32 v48, 0xbfb8aa3b, v45
	v_mul_f32_e32 v49, 0xbfb8aa3b, v36
	v_mul_f32_e32 v52, 0xbfb8aa3b, v37
	v_exp_f32_e32 v39, v39
	v_exp_f32_e32 v48, v48
	v_exp_f32_e32 v49, v49
	v_exp_f32_e32 v52, v52
	v_add_f32_e32 v39, 1.0, v39
	v_add_f32_e32 v53, 1.0, v48
	v_add_f32_e32 v58, 1.0, v49
	v_add_f32_e32 v59, 1.0, v52
	v_rcp_f32_e32 v48, v39
	v_rcp_f32_e32 v49, v53
	v_rcp_f32_e32 v52, v58
	v_rcp_f32_e32 v53, v59
	v_pk_mul_f32 v[44:45], v[48:49], v[44:45]
	v_pk_mul_f32 v[48:49], v[56:57], v[20:21] op_sel_hi:[1,0]
	v_pk_mul_f32 v[36:37], v[52:53], v[36:37]
	v_pk_mul_f32 v[12:13], v[12:13], v[48:49]
	v_pk_mul_f32 v[10:11], v[44:45], v[10:11]
	v_pk_mul_f32 v[12:13], v[36:37], v[12:13]
	v_cvt_pk_bf16_f32 v10, v10, v11
	v_cvt_pk_bf16_f32 v11, v12, v13
	global_store_dwordx2 v[26:27], v[10:11], off offset:256
	s_waitcnt vmcnt(6)
	v_mov_b32_e32 v10, v212
	v_mov_b32_e32 v11, v213
	v_mov_b32_e32 v12, v214
	v_mov_b32_e32 v13, v215
	s_nop 0
	v_cvt_f32_f16_e32 v36, v42
	v_cvt_f32_f16_sdwa v37, v42 dst_sel:DWORD dst_unused:UNUSED_PAD src0_sel:WORD_1
	v_cvt_f32_f16_e32 v42, v43
	v_cvt_f32_f16_sdwa v43, v43 dst_sel:DWORD dst_unused:UNUSED_PAD src0_sel:WORD_1
	v_mul_f32_e32 v39, 0xbfb8aa3b, v36
	v_mul_f32_e32 v44, 0xbfb8aa3b, v37
	v_mul_f32_e32 v45, 0xbfb8aa3b, v42
	v_mul_f32_e32 v48, 0xbfb8aa3b, v43
	v_exp_f32_e32 v39, v39
	v_exp_f32_e32 v44, v44
	v_exp_f32_e32 v45, v45
	v_exp_f32_e32 v48, v48
	v_add_f32_e32 v39, 1.0, v39
	v_add_f32_e32 v49, 1.0, v44
	v_add_f32_e32 v52, 1.0, v45
	v_add_f32_e32 v53, 1.0, v48
	v_rcp_f32_e32 v44, v39
	v_rcp_f32_e32 v45, v49
	v_rcp_f32_e32 v48, v52
	v_rcp_f32_e32 v49, v53
	v_pk_mul_f32 v[36:37], v[44:45], v[36:37]
	v_pk_mul_f32 v[44:45], v[54:55], v[20:21] op_sel_hi:[1,0]
	v_pk_mul_f32 v[42:43], v[48:49], v[42:43]
	s_nop 0
	v_pk_mul_f32 v[10:11], v[10:11], v[28:29]
	v_pk_mul_f32 v[12:13], v[12:13], v[44:45]
	v_pk_mul_f32 v[10:11], v[36:37], v[10:11]
	v_pk_mul_f32 v[12:13], v[42:43], v[12:13]
	v_cvt_pk_bf16_f32 v10, v10, v11
	v_cvt_pk_bf16_f32 v11, v12, v13
	global_store_dwordx2 v[26:27], v[10:11], off offset:288
	s_waitcnt vmcnt(5)
; __device__ __forceinline__ float siluf(float x) { return x * __builtin_amdgcn_rcpf(1.f + ex2(x * -1.44269504f)); }
; __device__ __forceinline__ void ret_out_item(const Params& p, int l, LAS unsigned char* lds, int item, int tid, int wave, int lane) {
;     ...
; #pragma unroll
;     for (int dvt = 0; dvt < 16; ++dvt) { const int col = h * 256 + dvt * 16 + 4 * g;
;         const f32x4 gw = *(const f32x4*)(p.gn_w + l * DM + col); const h4 rg = *(const h4*)(PR + (size_t)tok * NIN + C_RG + col);
;         h4 y;
; #pragma unroll
;         for (int e = 0; e < 4; ++e) y[e] = op16(o[dvt][e] * rstd * gw[e] * siluf((float)rg[e]), TAIL_BF16);
;         *(h4*)(RA + (size_t)tok * 4096 + col) = y; }
	v_mov_b32_e32 v10, v216
	v_mov_b32_e32 v11, v217
	v_mov_b32_e32 v12, v218
	v_mov_b32_e32 v13, v219
	v_mov_b32_e32 v29, v3
	v_or_b32_e32 v28, 0x160, v38
	v_lshl_add_u64 v[28:29], v[30:31], 0, v[28:29]
	v_mov_b32_e32 v28, v118
	v_mov_b32_e32 v29, v119
	v_cvt_f32_f16_e32 v36, v32
	v_cvt_f32_f16_sdwa v37, v32 dst_sel:DWORD dst_unused:UNUSED_PAD src0_sel:WORD_1
	v_cvt_f32_f16_e32 v32, v33
	v_cvt_f32_f16_sdwa v33, v33 dst_sel:DWORD dst_unused:UNUSED_PAD src0_sel:WORD_1
	v_mul_f32_e32 v39, 0xbfb8aa3b, v36
	v_mul_f32_e32 v42, 0xbfb8aa3b, v37
	v_mul_f32_e32 v43, 0xbfb8aa3b, v32
	v_mul_f32_e32 v44, 0xbfb8aa3b, v33
	v_exp_f32_e32 v39, v39
	v_exp_f32_e32 v42, v42
	v_exp_f32_e32 v43, v43
	v_exp_f32_e32 v44, v44
	v_add_f32_e32 v39, 1.0, v39
	v_add_f32_e32 v45, 1.0, v42
	v_add_f32_e32 v48, 1.0, v43
	v_add_f32_e32 v49, 1.0, v44
	v_rcp_f32_e32 v42, v39
	v_rcp_f32_e32 v43, v45
	v_rcp_f32_e32 v44, v48
	v_rcp_f32_e32 v45, v49
	v_pk_mul_f32 v[36:37], v[42:43], v[36:37]
	v_pk_mul_f32 v[42:43], v[50:51], v[20:21] op_sel_hi:[1,0]
	v_pk_mul_f32 v[32:33], v[44:45], v[32:33]
	s_nop 0
	v_pk_mul_f32 v[10:11], v[10:11], v[42:43]
	v_pk_mul_f32 v[12:13], v[12:13], v[22:23]
	v_pk_mul_f32 v[10:11], v[36:37], v[10:11]
	v_pk_mul_f32 v[12:13], v[32:33], v[12:13]
	v_cvt_pk_bf16_f32 v10, v10, v11
	v_cvt_pk_bf16_f32 v11, v12, v13
	global_store_dwordx2 v[26:27], v[10:11], off offset:320
	s_waitcnt vmcnt(4)
	v_mov_b32_e32 v10, v220
	v_mov_b32_e32 v11, v221
	v_mov_b32_e32 v12, v222
	v_mov_b32_e32 v13, v223
	s_nop 0
	v_cvt_f32_f16_e32 v32, v28
	v_cvt_f32_f16_sdwa v33, v28 dst_sel:DWORD dst_unused:UNUSED_PAD src0_sel:WORD_1
	v_cvt_f32_f16_e32 v28, v29
	v_cvt_f32_f16_sdwa v29, v29 dst_sel:DWORD dst_unused:UNUSED_PAD src0_sel:WORD_1
	v_mul_f32_e32 v36, 0xbfb8aa3b, v32
	v_mul_f32_e32 v37, 0xbfb8aa3b, v33
	v_mul_f32_e32 v39, 0xbfb8aa3b, v28
	v_mul_f32_e32 v42, 0xbfb8aa3b, v29
	v_exp_f32_e32 v36, v36
	v_exp_f32_e32 v37, v37
	v_exp_f32_e32 v39, v39
	v_exp_f32_e32 v42, v42
	v_add_f32_e32 v36, 1.0, v36
	v_add_f32_e32 v37, 1.0, v37
	v_add_f32_e32 v39, 1.0, v39
	v_add_f32_e32 v43, 1.0, v42
	v_rcp_f32_e32 v36, v36
	v_rcp_f32_e32 v37, v37
	v_rcp_f32_e32 v42, v39
	v_rcp_f32_e32 v43, v43
	v_mov_b32_e32 v23, v3
	v_pk_mul_f32 v[32:33], v[36:37], v[32:33]
	v_pk_mul_f32 v[36:37], v[46:47], v[20:21] op_sel_hi:[1,0]
	v_pk_mul_f32 v[28:29], v[42:43], v[28:29]
	v_or_b32_e32 v22, 0x180, v38
	v_lshl_add_u64 v[22:23], v[30:31], 0, v[22:23]
	v_mov_b32_e32 v22, v120
	v_mov_b32_e32 v23, v121
	s_nop 0
	v_pk_mul_f32 v[10:11], v[10:11], v[24:25]
	v_pk_mul_f32 v[12:13], v[12:13], v[36:37]
	v_pk_mul_f32 v[10:11], v[32:33], v[10:11]
	v_pk_mul_f32 v[12:13], v[28:29], v[12:13]
	v_cvt_pk_bf16_f32 v10, v10, v11
	v_cvt_pk_bf16_f32 v11, v12, v13
	global_store_dwordx2 v[26:27], v[10:11], off offset:352
	s_waitcnt vmcnt(3)
	v_mov_b32_e32 v10, v224
	v_mov_b32_e32 v11, v225
	v_mov_b32_e32 v12, v226
	v_mov_b32_e32 v13, v227
	v_mov_b32_e32 v25, v3
	v_or_b32_e32 v24, 0x1a0, v38
	v_lshl_add_u64 v[24:25], v[30:31], 0, v[24:25]
	v_mov_b32_e32 v24, v122
	v_mov_b32_e32 v25, v123
	s_nop 0
	v_pk_mul_f32 v[10:11], v[10:11], v[16:17]
	v_mov_b32_e32 v17, v3
	v_or_b32_e32 v16, 0x1c0, v38
	v_lshl_add_u64 v[16:17], v[30:31], 0, v[16:17]
	v_mov_b32_e32 v16, v206
	v_mov_b32_e32 v17, v207
	v_cvt_f32_f16_e32 v28, v22
	v_cvt_f32_f16_sdwa v29, v22 dst_sel:DWORD dst_unused:UNUSED_PAD src0_sel:WORD_1
	v_cvt_f32_f16_e32 v22, v23
	v_cvt_f32_f16_sdwa v23, v23 dst_sel:DWORD dst_unused:UNUSED_PAD src0_sel:WORD_1
	v_mul_f32_e32 v32, 0xbfb8aa3b, v28
	v_mul_f32_e32 v33, 0xbfb8aa3b, v29
	v_mul_f32_e32 v36, 0xbfb8aa3b, v22
	v_mul_f32_e32 v37, 0xbfb8aa3b, v23
	v_exp_f32_e32 v32, v32
	v_exp_f32_e32 v33, v33
	v_exp_f32_e32 v36, v36
	v_exp_f32_e32 v37, v37
	v_add_f32_e32 v32, 1.0, v32
	v_add_f32_e32 v33, 1.0, v33
	v_add_f32_e32 v36, 1.0, v36
	v_add_f32_e32 v37, 1.0, v37
	v_rcp_f32_e32 v32, v32
	v_rcp_f32_e32 v33, v33
	v_rcp_f32_e32 v36, v36
	v_rcp_f32_e32 v37, v37
	v_pk_mul_f32 v[28:29], v[32:33], v[28:29]
	v_pk_mul_f32 v[32:33], v[40:41], v[20:21] op_sel_hi:[1,0]
	v_pk_mul_f32 v[22:23], v[36:37], v[22:23]
	v_pk_mul_f32 v[12:13], v[12:13], v[32:33]
	v_pk_mul_f32 v[10:11], v[28:29], v[10:11]
	v_pk_mul_f32 v[12:13], v[22:23], v[12:13]
	v_cvt_pk_bf16_f32 v10, v10, v11
	v_cvt_pk_bf16_f32 v11, v12, v13
	global_store_dwordx2 v[26:27], v[10:11], off offset:384
	s_waitcnt vmcnt(2)
; __device__ __forceinline__ float siluf(float x) { return x * __builtin_amdgcn_rcpf(1.f + ex2(x * -1.44269504f)); }
; __device__ __forceinline__ void ret_out_item(const Params& p, int l, LAS unsigned char* lds, int item, int tid, int wave, int lane) {
;     ...
; #pragma unroll
;     for (int dvt = 0; dvt < 16; ++dvt) { const int col = h * 256 + dvt * 16 + 4 * g;
;         const f32x4 gw = *(const f32x4*)(p.gn_w + l * DM + col); const h4 rg = *(const h4*)(PR + (size_t)tok * NIN + C_RG + col);
;         h4 y;
; #pragma unroll
;         for (int e = 0; e < 4; ++e) y[e] = op16(o[dvt][e] * rstd * gw[e] * siluf((float)rg[e]), TAIL_BF16);
;         *(h4*)(RA + (size_t)tok * 4096 + col) = y; }
;     __syncthreads();
	v_mov_b32_e32 v10, v228
	v_mov_b32_e32 v11, v229
	v_mov_b32_e32 v12, v230
	v_mov_b32_e32 v13, v231
	s_nop 0
	v_cvt_f32_f16_e32 v22, v24
	v_cvt_f32_f16_sdwa v23, v24 dst_sel:DWORD dst_unused:UNUSED_PAD src0_sel:WORD_1
	v_cvt_f32_f16_e32 v24, v25
	v_cvt_f32_f16_sdwa v25, v25 dst_sel:DWORD dst_unused:UNUSED_PAD src0_sel:WORD_1
	v_mul_f32_e32 v28, 0xbfb8aa3b, v22
	v_mul_f32_e32 v29, 0xbfb8aa3b, v23
	v_mul_f32_e32 v32, 0xbfb8aa3b, v24
	v_mul_f32_e32 v33, 0xbfb8aa3b, v25
	v_exp_f32_e32 v28, v28
	v_exp_f32_e32 v29, v29
	v_exp_f32_e32 v32, v32
	v_exp_f32_e32 v33, v33
	v_add_f32_e32 v28, 1.0, v28
	v_add_f32_e32 v29, 1.0, v29
	v_add_f32_e32 v32, 1.0, v32
	v_add_f32_e32 v33, 1.0, v33
	v_rcp_f32_e32 v28, v28
	v_rcp_f32_e32 v29, v29
	v_rcp_f32_e32 v32, v32
	v_rcp_f32_e32 v33, v33
	v_pk_mul_f32 v[22:23], v[28:29], v[22:23]
	v_pk_mul_f32 v[28:29], v[34:35], v[20:21] op_sel_hi:[1,0]
	v_pk_mul_f32 v[24:25], v[32:33], v[24:25]
	s_nop 0
	v_pk_mul_f32 v[10:11], v[10:11], v[28:29]
	v_pk_mul_f32 v[12:13], v[12:13], v[14:15]
	v_pk_mul_f32 v[10:11], v[22:23], v[10:11]
	v_pk_mul_f32 v[12:13], v[24:25], v[12:13]
	v_cvt_pk_bf16_f32 v10, v10, v11
	v_cvt_pk_bf16_f32 v11, v12, v13
	global_store_dwordx2 v[26:27], v[10:11], off offset:416
	s_waitcnt vmcnt(1)
	v_mov_b32_e32 v10, v232
	v_mov_b32_e32 v11, v233
	v_mov_b32_e32 v12, v234
	v_mov_b32_e32 v13, v235
	v_mov_b32_e32 v15, v3
	v_or_b32_e32 v14, 0x1e0, v38
	v_lshl_add_u64 v[14:15], v[30:31], 0, v[14:15]
	v_mov_b32_e32 v14, v102
	v_mov_b32_e32 v15, v103
	v_cvt_f32_f16_e32 v22, v16
	v_cvt_f32_f16_sdwa v23, v16 dst_sel:DWORD dst_unused:UNUSED_PAD src0_sel:WORD_1
	v_cvt_f32_f16_e32 v16, v17
	v_cvt_f32_f16_sdwa v17, v17 dst_sel:DWORD dst_unused:UNUSED_PAD src0_sel:WORD_1
	v_mul_f32_e32 v24, 0xbfb8aa3b, v22
	v_mul_f32_e32 v25, 0xbfb8aa3b, v23
	v_mul_f32_e32 v28, 0xbfb8aa3b, v16
	v_mul_f32_e32 v29, 0xbfb8aa3b, v17
	v_exp_f32_e32 v24, v24
	v_exp_f32_e32 v25, v25
	v_exp_f32_e32 v28, v28
	v_exp_f32_e32 v29, v29
	v_add_f32_e32 v24, 1.0, v24
	v_add_f32_e32 v25, 1.0, v25
	v_add_f32_e32 v28, 1.0, v28
	v_add_f32_e32 v29, 1.0, v29
	v_rcp_f32_e32 v24, v24
	v_rcp_f32_e32 v25, v25
	v_rcp_f32_e32 v28, v28
	v_rcp_f32_e32 v29, v29
	v_pk_mul_f32 v[22:23], v[24:25], v[22:23]
	v_pk_mul_f32 v[16:17], v[28:29], v[16:17]
	s_nop 0
	v_pk_mul_f32 v[8:9], v[10:11], v[8:9]
	v_pk_mul_f32 v[10:11], v[12:13], v[18:19]
	v_pk_mul_f32 v[8:9], v[8:9], v[22:23]
	v_pk_mul_f32 v[10:11], v[10:11], v[16:17]
	v_cvt_pk_bf16_f32 v8, v8, v9
	v_cvt_pk_bf16_f32 v9, v10, v11
	global_store_dwordx2 v[26:27], v[8:9], off offset:448
	s_waitcnt vmcnt(0)
	v_mov_b32_e32 v8, v236
	v_mov_b32_e32 v9, v237
	v_mov_b32_e32 v10, v238
	v_mov_b32_e32 v11, v239
	s_nop 0
	v_cvt_f32_f16_e32 v12, v14
	v_cvt_f32_f16_sdwa v13, v14 dst_sel:DWORD dst_unused:UNUSED_PAD src0_sel:WORD_1
	v_cvt_f32_f16_e32 v14, v15
	v_cvt_f32_f16_sdwa v15, v15 dst_sel:DWORD dst_unused:UNUSED_PAD src0_sel:WORD_1
	v_mul_f32_e32 v16, 0xbfb8aa3b, v12
	v_mul_f32_e32 v17, 0xbfb8aa3b, v13
	v_mul_f32_e32 v18, 0xbfb8aa3b, v14
	v_mul_f32_e32 v19, 0xbfb8aa3b, v15
	v_exp_f32_e32 v16, v16
	v_exp_f32_e32 v17, v17
	v_exp_f32_e32 v18, v18
	v_exp_f32_e32 v19, v19
	v_add_f32_e32 v16, 1.0, v16
	v_add_f32_e32 v17, 1.0, v17
	v_add_f32_e32 v18, 1.0, v18
	v_add_f32_e32 v19, 1.0, v19
	v_rcp_f32_e32 v16, v16
	v_rcp_f32_e32 v17, v17
	v_rcp_f32_e32 v18, v18
	v_rcp_f32_e32 v19, v19
	v_pk_mul_f32 v[12:13], v[16:17], v[12:13]
	v_pk_mul_f32 v[14:15], v[18:19], v[14:15]
	s_nop 0
	v_pk_mul_f32 v[4:5], v[8:9], v[4:5]
	v_pk_mul_f32 v[6:7], v[10:11], v[6:7]
	v_pk_mul_f32 v[4:5], v[4:5], v[12:13]
	v_pk_mul_f32 v[6:7], v[6:7], v[14:15]
	v_cvt_pk_bf16_f32 v4, v4, v5
	v_cvt_pk_bf16_f32 v5, v6, v7
	global_store_dwordx2 v[26:27], v[4:5], off offset:480
	s_barrier
	s_cbranch_scc1 .LBB0_534
